# v63 + grid barrier: per-XCD release word dropped entirely (leaders no longer do the extra atomic + wait after the release; first check also reads the cross-XCD generation)
# baseline (speedup 1.0000x reference)
; __device__ __forceinline__ unsigned xb_ld(unsigned* p)              { return __hip_atomic_load(p, __ATOMIC_RELAXED, __HIP_MEMORY_SCOPE_AGENT); }
; __device__ __forceinline__ unsigned xb_add(unsigned* p, unsigned v) { return __hip_atomic_fetch_add(p, v, __ATOMIC_RELAXED, __HIP_MEMORY_SCOPE_AGENT); }
; #define XB_SPIN(cond, bar) do { unsigned _sp = 0; while (cond) { __builtin_amdgcn_s_sleep(1); \
;     if ((++_sp & 255u) == 0u) { if (xb_ld(&(bar)[XB_TMO])) break; if (_sp > XB_SPIN_CAP) { atomicAdd(&(bar)[XB_TMO], 1u); break; } } } } while (0)
; __device__ __forceinline__ void xcd_barrier(const XcdBarrier& b) {
;     ...
;         const unsigned old = xb_add(&bar[XB_XSUB(b.x)], 1u);
;         const unsigned gen = old / nloc;
;         if (old + 1u == (gen + 1u) * nloc) {
;             __builtin_amdgcn_fence(__ATOMIC_RELEASE, "agent");
;             asm volatile("s_waitcnt vmcnt(0)" ::: "memory");
;             const unsigned og = xb_add(&bar[XB_TOP], 1u);
;             const unsigned tg = og / nx;
;             if (og + 1u == (tg + 1u) * nx) xb_add(&bar[XB_TOPGEN], 1u);
;             else XB_SPIN(xb_ld(&bar[XB_TOPGEN]) == tg, bar);
;             __builtin_amdgcn_fence(__ATOMIC_ACQUIRE, "agent");
;             xb_add(&bar[XB_XGEN(b.x)], 1u);
;             asm volatile("s_waitcnt vmcnt(0)" ::: "memory");
;         } else {
;             XB_SPIN(xb_ld(&bar[XB_XGEN(b.x)]) == gen, bar);
.LBB0_216:
	s_lshl_b32 s74, s68, 6
	s_lshl_b64 s[4:5], s[74:75], 2
	s_add_u32 s8, s88, s4
	s_addc_u32 s9, s89, s5
	v_mov_b32_e32 v1, 0x1000
	global_atomic_add v4, v1, v252, s[8:9] offset:1024 sc0
	v_cvt_f32_u32_e32 v1, v3
	v_sub_u32_e32 v5, 0, v3
	v_rcp_iflag_f32_e32 v1, v1
	s_nop 0
	v_mul_f32_e32 v1, 0x4f7ffffe, v1
	v_cvt_u32_f32_e32 v1, v1
	v_mul_lo_u32 v5, v5, v1
	v_mul_hi_u32 v5, v1, v5
	v_add_u32_e32 v1, v1, v5
	s_waitcnt vmcnt(0)
	v_mul_hi_u32 v1, v4, v1
	v_mul_lo_u32 v5, v1, v3
	v_sub_u32_e32 v5, v4, v5
	v_add_u32_e32 v6, 1, v1
	v_cmp_ge_u32_e32 vcc, v5, v3
	v_add_u32_e32 v4, 1, v4
	s_nop 0
	v_cndmask_b32_e32 v1, v1, v6, vcc
	v_sub_u32_e32 v6, v5, v3
	v_cndmask_b32_e32 v5, v5, v6, vcc
	v_add_u32_e32 v6, 1, v1
	v_cmp_ge_u32_e32 vcc, v5, v3
	s_nop 1
	v_cndmask_b32_e32 v1, v1, v6, vcc
	v_mul_lo_u32 v5, v3, v1
	v_add_u32_e32 v3, v5, v3
	v_cmp_ne_u32_e32 vcc, v4, v3
	s_and_saveexec_b64 s[4:5], vcc
	s_xor_b64 s[10:11], exec, s[4:5]
	s_cbranch_execz .LBB0_229
	s_waitcnt lgkmcnt(0)
	s_add_u32 s14, s88, 0x3500
	s_addc_u32 s15, s89, 0
	global_load_dword v2, v0, s[14:15] sc1
	s_waitcnt vmcnt(0)
	v_cmp_eq_u32_e32 vcc, v2, v1
	s_and_saveexec_b64 s[12:13], vcc
	s_cbranch_execz .LBB0_228
	s_mov_b32 s4, 1
	s_mov_b64 s[16:17], 0
	s_branch .LBB0_220

; __device__ __forceinline__ unsigned xb_ld(unsigned* p)              { return __hip_atomic_load(p, __ATOMIC_RELAXED, __HIP_MEMORY_SCOPE_AGENT); }
; __device__ __forceinline__ unsigned xb_add(unsigned* p, unsigned v) { return __hip_atomic_fetch_add(p, v, __ATOMIC_RELAXED, __HIP_MEMORY_SCOPE_AGENT); }
; #define XB_SPIN(cond, bar) do { unsigned _sp = 0; while (cond) { __builtin_amdgcn_s_sleep(1); \
;     if ((++_sp & 255u) == 0u) { if (xb_ld(&(bar)[XB_TMO])) break; if (_sp > XB_SPIN_CAP) { atomicAdd(&(bar)[XB_TMO], 1u); break; } } } } while (0)
; __device__ __forceinline__ void xcd_barrier(const XcdBarrier& b) {
;     ...
;             const unsigned og = xb_add(&bar[XB_TOP], 1u);
;             const unsigned tg = og / nx;
;             if (og + 1u == (tg + 1u) * nx) xb_add(&bar[XB_TOPGEN], 1u);
;             else XB_SPIN(xb_ld(&bar[XB_TOPGEN]) == tg, bar);
;             __builtin_amdgcn_fence(__ATOMIC_ACQUIRE, "agent");
;             xb_add(&bar[XB_XGEN(b.x)], 1u);
;             asm volatile("s_waitcnt vmcnt(0)" ::: "memory");
.LBB0_242:
	s_or_b64 exec, exec, s[12:13]
	s_and_saveexec_b64 s[10:11], s[14:15]
	s_cbranch_execz .LBB0_244
	global_atomic_add v[2:3], v252, off
.LBB0_244:
	s_or_b64 exec, exec, s[10:11]
	s_waitcnt vmcnt(0)
	buffer_inv sc1
	s_waitcnt vmcnt(0)
.LBB0_245:
	s_or_b64 exec, exec, s[6:7]
	s_waitcnt lgkmcnt(0)
	s_barrier
	s_mov_b32 s90, s68
	s_branch .LBB0_260

; __device__ __forceinline__ unsigned xb_ld(unsigned* p)              { return __hip_atomic_load(p, __ATOMIC_RELAXED, __HIP_MEMORY_SCOPE_AGENT); }
; __device__ __forceinline__ unsigned xb_add(unsigned* p, unsigned v) { return __hip_atomic_fetch_add(p, v, __ATOMIC_RELAXED, __HIP_MEMORY_SCOPE_AGENT); }
; #define XB_SPIN(cond, bar) do { unsigned _sp = 0; while (cond) { __builtin_amdgcn_s_sleep(1); \
;     if ((++_sp & 255u) == 0u) { if (xb_ld(&(bar)[XB_TMO])) break; if (_sp > XB_SPIN_CAP) { atomicAdd(&(bar)[XB_TMO], 1u); break; } } } } while (0)
; __device__ __forceinline__ void xcd_barrier(const XcdBarrier& b) {
;     ...
;         const unsigned old = xb_add(&bar[XB_XSUB(b.x)], 1u);
;         const unsigned gen = old / nloc;
;         if (old + 1u == (gen + 1u) * nloc) {
;             __builtin_amdgcn_fence(__ATOMIC_RELEASE, "agent");
;             asm volatile("s_waitcnt vmcnt(0)" ::: "memory");
;             const unsigned og = xb_add(&bar[XB_TOP], 1u);
;             const unsigned tg = og / nx;
;             if (og + 1u == (tg + 1u) * nx) xb_add(&bar[XB_TOPGEN], 1u);
;             else XB_SPIN(xb_ld(&bar[XB_TOPGEN]) == tg, bar);
;             __builtin_amdgcn_fence(__ATOMIC_ACQUIRE, "agent");
;             xb_add(&bar[XB_XGEN(b.x)], 1u);
;             asm volatile("s_waitcnt vmcnt(0)" ::: "memory");
;         } else {
;             XB_SPIN(xb_ld(&bar[XB_XGEN(b.x)]) == gen, bar);
.LBB0_310:
	s_lshl_b32 s74, s90, 6
	s_lshl_b64 s[4:5], s[74:75], 2
	s_add_u32 s8, s88, s4
	s_addc_u32 s9, s89, s5
	v_mov_b32_e32 v1, 0x1000
	global_atomic_add v4, v1, v252, s[8:9] offset:1024 sc0
	v_cvt_f32_u32_e32 v1, v3
	v_sub_u32_e32 v5, 0, v3
	v_rcp_iflag_f32_e32 v1, v1
	s_nop 0
	v_mul_f32_e32 v1, 0x4f7ffffe, v1
	v_cvt_u32_f32_e32 v1, v1
	v_mul_lo_u32 v5, v5, v1
	v_mul_hi_u32 v5, v1, v5
	v_add_u32_e32 v1, v1, v5
	s_waitcnt vmcnt(0)
	v_mul_hi_u32 v1, v4, v1
	v_mul_lo_u32 v5, v1, v3
	v_sub_u32_e32 v5, v4, v5
	v_add_u32_e32 v6, 1, v1
	v_cmp_ge_u32_e32 vcc, v5, v3
	v_add_u32_e32 v4, 1, v4
	s_nop 0
	v_cndmask_b32_e32 v1, v1, v6, vcc
	v_sub_u32_e32 v6, v5, v3
	v_cndmask_b32_e32 v5, v5, v6, vcc
	v_add_u32_e32 v6, 1, v1
	v_cmp_ge_u32_e32 vcc, v5, v3
	s_nop 1
	v_cndmask_b32_e32 v1, v1, v6, vcc
	v_mul_lo_u32 v5, v3, v1
	v_add_u32_e32 v3, v5, v3
	v_cmp_ne_u32_e32 vcc, v4, v3
	s_and_saveexec_b64 s[4:5], vcc
	s_xor_b64 s[10:11], exec, s[4:5]
	s_cbranch_execz .LBB0_323
	s_waitcnt lgkmcnt(0)
	s_add_u32 s14, s88, 0x3500
	s_addc_u32 s15, s89, 0
	global_load_dword v2, v0, s[14:15] sc1
	s_waitcnt vmcnt(0)
	v_cmp_eq_u32_e32 vcc, v2, v1
	s_and_saveexec_b64 s[12:13], vcc
	s_cbranch_execz .LBB0_322
	s_mov_b32 s2, 1
	s_mov_b64 s[16:17], 0
	s_branch .LBB0_314

; __device__ __forceinline__ unsigned xb_ld(unsigned* p)              { return __hip_atomic_load(p, __ATOMIC_RELAXED, __HIP_MEMORY_SCOPE_AGENT); }
; __device__ __forceinline__ unsigned xb_add(unsigned* p, unsigned v) { return __hip_atomic_fetch_add(p, v, __ATOMIC_RELAXED, __HIP_MEMORY_SCOPE_AGENT); }
; #define XB_SPIN(cond, bar) do { unsigned _sp = 0; while (cond) { __builtin_amdgcn_s_sleep(1); \
;     if ((++_sp & 255u) == 0u) { if (xb_ld(&(bar)[XB_TMO])) break; if (_sp > XB_SPIN_CAP) { atomicAdd(&(bar)[XB_TMO], 1u); break; } } } } while (0)
; __device__ __forceinline__ void xcd_barrier(const XcdBarrier& b) {
;     ...
;             if (og + 1u == (tg + 1u) * nx) xb_add(&bar[XB_TOPGEN], 1u);
;             else XB_SPIN(xb_ld(&bar[XB_TOPGEN]) == tg, bar);
;             __builtin_amdgcn_fence(__ATOMIC_ACQUIRE, "agent");
;             xb_add(&bar[XB_XGEN(b.x)], 1u);
;             asm volatile("s_waitcnt vmcnt(0)" ::: "memory");
.LBB0_336:
	s_or_b64 exec, exec, s[12:13]
	s_and_saveexec_b64 s[10:11], s[14:15]
	s_cbranch_execz .LBB0_338
	global_atomic_add v[2:3], v252, off
.LBB0_338:
	s_or_b64 exec, exec, s[10:11]
	s_waitcnt vmcnt(0)
	buffer_inv sc1
	s_waitcnt vmcnt(0)
.LBB0_339:
	s_or_b64 exec, exec, s[6:7]
	s_waitcnt lgkmcnt(0)
	s_barrier
	s_branch .LBB0_354

; __device__ __forceinline__ unsigned xb_ld(unsigned* p)              { return __hip_atomic_load(p, __ATOMIC_RELAXED, __HIP_MEMORY_SCOPE_AGENT); }
; __device__ __forceinline__ unsigned xb_add(unsigned* p, unsigned v) { return __hip_atomic_fetch_add(p, v, __ATOMIC_RELAXED, __HIP_MEMORY_SCOPE_AGENT); }
; #define XB_SPIN(cond, bar) do { unsigned _sp = 0; while (cond) { __builtin_amdgcn_s_sleep(1); \
;     if ((++_sp & 255u) == 0u) { if (xb_ld(&(bar)[XB_TMO])) break; if (_sp > XB_SPIN_CAP) { atomicAdd(&(bar)[XB_TMO], 1u); break; } } } } while (0)
; __device__ __forceinline__ void xcd_barrier(const XcdBarrier& b) {
;     ...
;         const unsigned old = xb_add(&bar[XB_XSUB(b.x)], 1u);
;         const unsigned gen = old / nloc;
;         if (old + 1u == (gen + 1u) * nloc) {
;             __builtin_amdgcn_fence(__ATOMIC_RELEASE, "agent");
;             asm volatile("s_waitcnt vmcnt(0)" ::: "memory");
;             const unsigned og = xb_add(&bar[XB_TOP], 1u);
;             const unsigned tg = og / nx;
;             if (og + 1u == (tg + 1u) * nx) xb_add(&bar[XB_TOPGEN], 1u);
;             else XB_SPIN(xb_ld(&bar[XB_TOPGEN]) == tg, bar);
;             __builtin_amdgcn_fence(__ATOMIC_ACQUIRE, "agent");
;             xb_add(&bar[XB_XGEN(b.x)], 1u);
;             asm volatile("s_waitcnt vmcnt(0)" ::: "memory");
;         } else {
;             XB_SPIN(xb_ld(&bar[XB_XGEN(b.x)]) == gen, bar);
.LBB0_573:
	s_lshl_b32 s74, s90, 6
	s_lshl_b64 s[4:5], s[74:75], 2
	s_add_u32 s6, s88, s4
	s_addc_u32 s7, s89, s5
	v_mov_b32_e32 v1, 0x1000
	global_atomic_add v4, v1, v252, s[6:7] offset:1024 sc0
	v_cvt_f32_u32_e32 v1, v3
	v_sub_u32_e32 v5, 0, v3
	v_rcp_iflag_f32_e32 v1, v1
	s_nop 0
	v_mul_f32_e32 v1, 0x4f7ffffe, v1
	v_cvt_u32_f32_e32 v1, v1
	v_mul_lo_u32 v5, v5, v1
	v_mul_hi_u32 v5, v1, v5
	v_add_u32_e32 v1, v1, v5
	s_waitcnt vmcnt(0)
	v_mul_hi_u32 v1, v4, v1
	v_mul_lo_u32 v5, v1, v3
	v_sub_u32_e32 v5, v4, v5
	v_add_u32_e32 v6, 1, v1
	v_cmp_ge_u32_e32 vcc, v5, v3
	v_add_u32_e32 v4, 1, v4
	s_nop 0
	v_cndmask_b32_e32 v1, v1, v6, vcc
	v_sub_u32_e32 v6, v5, v3
	v_cndmask_b32_e32 v5, v5, v6, vcc
	v_add_u32_e32 v6, 1, v1
	v_cmp_ge_u32_e32 vcc, v5, v3
	s_nop 1
	v_cndmask_b32_e32 v1, v1, v6, vcc
	v_mul_lo_u32 v5, v3, v1
	v_add_u32_e32 v3, v5, v3
	v_cmp_ne_u32_e32 vcc, v4, v3
	s_and_saveexec_b64 s[4:5], vcc
	s_xor_b64 s[8:9], exec, s[4:5]
	s_cbranch_execz .LBB0_586
	s_waitcnt lgkmcnt(0)
	s_add_u32 s12, s88, 0x3500
	s_addc_u32 s13, s89, 0
	global_load_dword v2, v0, s[12:13] sc1
	s_waitcnt vmcnt(0)
	v_cmp_eq_u32_e32 vcc, v2, v1
	s_and_saveexec_b64 s[10:11], vcc
	s_cbranch_execz .LBB0_585
	s_mov_b32 s4, 1
	s_mov_b64 s[14:15], 0
	s_branch .LBB0_577

; __device__ __forceinline__ unsigned xb_ld(unsigned* p)              { return __hip_atomic_load(p, __ATOMIC_RELAXED, __HIP_MEMORY_SCOPE_AGENT); }
; __device__ __forceinline__ unsigned xb_add(unsigned* p, unsigned v) { return __hip_atomic_fetch_add(p, v, __ATOMIC_RELAXED, __HIP_MEMORY_SCOPE_AGENT); }
; #define XB_SPIN(cond, bar) do { unsigned _sp = 0; while (cond) { __builtin_amdgcn_s_sleep(1); \
;     if ((++_sp & 255u) == 0u) { if (xb_ld(&(bar)[XB_TMO])) break; if (_sp > XB_SPIN_CAP) { atomicAdd(&(bar)[XB_TMO], 1u); break; } } } } while (0)
; __device__ __forceinline__ void xcd_barrier(const XcdBarrier& b) {
;     ...
;             if (og + 1u == (tg + 1u) * nx) xb_add(&bar[XB_TOPGEN], 1u);
;             else XB_SPIN(xb_ld(&bar[XB_TOPGEN]) == tg, bar);
;             __builtin_amdgcn_fence(__ATOMIC_ACQUIRE, "agent");
;             xb_add(&bar[XB_XGEN(b.x)], 1u);
;             asm volatile("s_waitcnt vmcnt(0)" ::: "memory");
.LBB0_599:
	s_or_b64 exec, exec, s[10:11]
	s_and_saveexec_b64 s[8:9], s[12:13]
	s_cbranch_execz .LBB0_601
	global_atomic_add v[2:3], v252, off
.LBB0_601:
	s_or_b64 exec, exec, s[8:9]
	s_waitcnt vmcnt(0)
	buffer_inv sc1
	s_waitcnt vmcnt(0)
.LBB0_602:
	s_or_b64 exec, exec, s[0:1]
	s_waitcnt lgkmcnt(0)
	s_barrier
	s_branch .LBB0_617

; __device__ __forceinline__ unsigned xb_ld(unsigned* p)              { return __hip_atomic_load(p, __ATOMIC_RELAXED, __HIP_MEMORY_SCOPE_AGENT); }
; __device__ __forceinline__ unsigned xb_add(unsigned* p, unsigned v) { return __hip_atomic_fetch_add(p, v, __ATOMIC_RELAXED, __HIP_MEMORY_SCOPE_AGENT); }
; #define XB_SPIN(cond, bar) do { unsigned _sp = 0; while (cond) { __builtin_amdgcn_s_sleep(1); \
;     if ((++_sp & 255u) == 0u) { if (xb_ld(&(bar)[XB_TMO])) break; if (_sp > XB_SPIN_CAP) { atomicAdd(&(bar)[XB_TMO], 1u); break; } } } } while (0)
; __device__ __forceinline__ void xcd_barrier(const XcdBarrier& b) {
;     ...
;             if (og + 1u == (tg + 1u) * nx) xb_add(&bar[XB_TOPGEN], 1u);
;             else XB_SPIN(xb_ld(&bar[XB_TOPGEN]) == tg, bar);
;             __builtin_amdgcn_fence(__ATOMIC_ACQUIRE, "agent");
;             xb_add(&bar[XB_XGEN(b.x)], 1u);
;             asm volatile("s_waitcnt vmcnt(0)" ::: "memory");
.LBB0_774:
	s_or_b64 exec, exec, s[12:13]
	s_and_saveexec_b64 s[10:11], s[14:15]
	s_cbranch_execz .LBB0_776
	global_atomic_add v[2:3], v252, off
.LBB0_776:
	s_or_b64 exec, exec, s[10:11]
	s_waitcnt vmcnt(0)
	buffer_inv sc1
	s_waitcnt vmcnt(0)
.LBB0_777:
	s_or_b64 exec, exec, s[6:7]
	s_waitcnt lgkmcnt(0)
	s_barrier
	s_mov_b64 s[6:7], 0

; __device__ __forceinline__ unsigned xb_ld(unsigned* p)              { return __hip_atomic_load(p, __ATOMIC_RELAXED, __HIP_MEMORY_SCOPE_AGENT); }
; __device__ __forceinline__ unsigned xb_add(unsigned* p, unsigned v) { return __hip_atomic_fetch_add(p, v, __ATOMIC_RELAXED, __HIP_MEMORY_SCOPE_AGENT); }
; #define XB_SPIN(cond, bar) do { unsigned _sp = 0; while (cond) { __builtin_amdgcn_s_sleep(1); \
;     if ((++_sp & 255u) == 0u) { if (xb_ld(&(bar)[XB_TMO])) break; if (_sp > XB_SPIN_CAP) { atomicAdd(&(bar)[XB_TMO], 1u); break; } } } } while (0)
; __device__ __forceinline__ void xcd_barrier(const XcdBarrier& b) {
;     ...
;             if (og + 1u == (tg + 1u) * nx) xb_add(&bar[XB_TOPGEN], 1u);
;             else XB_SPIN(xb_ld(&bar[XB_TOPGEN]) == tg, bar);
;             __builtin_amdgcn_fence(__ATOMIC_ACQUIRE, "agent");
;             xb_add(&bar[XB_XGEN(b.x)], 1u);
;             asm volatile("s_waitcnt vmcnt(0)" ::: "memory");
.LBB0_864:
	s_or_b64 exec, exec, s[12:13]
	s_and_saveexec_b64 s[10:11], s[14:15]
	s_cbranch_execz .LBB0_866
	global_atomic_add v[2:3], v252, off
.LBB0_866:
	s_or_b64 exec, exec, s[10:11]
	s_waitcnt vmcnt(0)
	buffer_inv sc1
	s_waitcnt vmcnt(0)
.LBB0_867:
	s_or_b64 exec, exec, s[6:7]
	s_waitcnt lgkmcnt(0)
	s_barrier
	s_branch .LBB0_882

; __device__ __forceinline__ unsigned xb_ld(unsigned* p)              { return __hip_atomic_load(p, __ATOMIC_RELAXED, __HIP_MEMORY_SCOPE_AGENT); }
; __device__ __forceinline__ unsigned xb_add(unsigned* p, unsigned v) { return __hip_atomic_fetch_add(p, v, __ATOMIC_RELAXED, __HIP_MEMORY_SCOPE_AGENT); }
; #define XB_SPIN(cond, bar) do { unsigned _sp = 0; while (cond) { __builtin_amdgcn_s_sleep(1); \
;     if ((++_sp & 255u) == 0u) { if (xb_ld(&(bar)[XB_TMO])) break; if (_sp > XB_SPIN_CAP) { atomicAdd(&(bar)[XB_TMO], 1u); break; } } } } while (0)
; __device__ __forceinline__ void xcd_barrier(const XcdBarrier& b) {
;     ...
;         const unsigned old = xb_add(&bar[XB_XSUB(b.x)], 1u);
;         const unsigned gen = old / nloc;
;         if (old + 1u == (gen + 1u) * nloc) {
;             __builtin_amdgcn_fence(__ATOMIC_RELEASE, "agent");
;             asm volatile("s_waitcnt vmcnt(0)" ::: "memory");
;             const unsigned og = xb_add(&bar[XB_TOP], 1u);
;             const unsigned tg = og / nx;
;             if (og + 1u == (tg + 1u) * nx) xb_add(&bar[XB_TOPGEN], 1u);
;             else XB_SPIN(xb_ld(&bar[XB_TOPGEN]) == tg, bar);
;             __builtin_amdgcn_fence(__ATOMIC_ACQUIRE, "agent");
;             xb_add(&bar[XB_XGEN(b.x)], 1u);
;             asm volatile("s_waitcnt vmcnt(0)" ::: "memory");
;         } else {
;             XB_SPIN(xb_ld(&bar[XB_XGEN(b.x)]) == gen, bar);
.LBB0_1015:
	s_lshl_b32 s74, s68, 6
	s_lshl_b64 s[4:5], s[74:75], 2
	s_add_u32 s8, s88, s4
	s_addc_u32 s9, s89, s5
	v_mov_b32_e32 v1, 0x1000
	global_atomic_add v4, v1, v252, s[8:9] offset:1024 sc0
	v_cvt_f32_u32_e32 v1, v3
	v_sub_u32_e32 v5, 0, v3
	v_rcp_iflag_f32_e32 v1, v1
	s_nop 0
	v_mul_f32_e32 v1, 0x4f7ffffe, v1
	v_cvt_u32_f32_e32 v1, v1
	v_mul_lo_u32 v5, v5, v1
	v_mul_hi_u32 v5, v1, v5
	v_add_u32_e32 v1, v1, v5
	s_waitcnt vmcnt(0)
	v_mul_hi_u32 v1, v4, v1
	v_mul_lo_u32 v5, v1, v3
	v_sub_u32_e32 v5, v4, v5
	v_add_u32_e32 v6, 1, v1
	v_cmp_ge_u32_e32 vcc, v5, v3
	v_add_u32_e32 v4, 1, v4
	s_nop 0
	v_cndmask_b32_e32 v1, v1, v6, vcc
	v_sub_u32_e32 v6, v5, v3
	v_cndmask_b32_e32 v5, v5, v6, vcc
	v_add_u32_e32 v6, 1, v1
	v_cmp_ge_u32_e32 vcc, v5, v3
	s_nop 1
	v_cndmask_b32_e32 v1, v1, v6, vcc
	v_mul_lo_u32 v5, v3, v1
	v_add_u32_e32 v3, v5, v3
	v_cmp_ne_u32_e32 vcc, v4, v3
	s_and_saveexec_b64 s[4:5], vcc
	s_xor_b64 s[10:11], exec, s[4:5]
	s_cbranch_execz .LBB0_1028
	s_waitcnt lgkmcnt(0)
	s_add_u32 s14, s88, 0x3500
	s_addc_u32 s15, s89, 0
	global_load_dword v2, v0, s[14:15] sc1
	s_waitcnt vmcnt(0)
	v_cmp_eq_u32_e32 vcc, v2, v1
	s_and_saveexec_b64 s[12:13], vcc
	s_cbranch_execz .LBB0_1027
	s_mov_b32 s2, 1
	s_mov_b64 s[16:17], 0
	s_branch .LBB0_1019

; __device__ __forceinline__ unsigned xb_ld(unsigned* p)              { return __hip_atomic_load(p, __ATOMIC_RELAXED, __HIP_MEMORY_SCOPE_AGENT); }
; __device__ __forceinline__ unsigned xb_add(unsigned* p, unsigned v) { return __hip_atomic_fetch_add(p, v, __ATOMIC_RELAXED, __HIP_MEMORY_SCOPE_AGENT); }
; #define XB_SPIN(cond, bar) do { unsigned _sp = 0; while (cond) { __builtin_amdgcn_s_sleep(1); \
;     if ((++_sp & 255u) == 0u) { if (xb_ld(&(bar)[XB_TMO])) break; if (_sp > XB_SPIN_CAP) { atomicAdd(&(bar)[XB_TMO], 1u); break; } } } } while (0)
; __device__ __forceinline__ void xcd_barrier(const XcdBarrier& b) {
;     ...
;             if (og + 1u == (tg + 1u) * nx) xb_add(&bar[XB_TOPGEN], 1u);
;             else XB_SPIN(xb_ld(&bar[XB_TOPGEN]) == tg, bar);
;             __builtin_amdgcn_fence(__ATOMIC_ACQUIRE, "agent");
;             xb_add(&bar[XB_XGEN(b.x)], 1u);
;             asm volatile("s_waitcnt vmcnt(0)" ::: "memory");
.LBB0_1041:
	s_or_b64 exec, exec, s[12:13]
	s_and_saveexec_b64 s[10:11], s[14:15]
	s_cbranch_execz .LBB0_1043
	global_atomic_add v[2:3], v252, off
.LBB0_1043:
	s_or_b64 exec, exec, s[10:11]
	s_waitcnt vmcnt(0)
	buffer_inv sc1
	s_waitcnt vmcnt(0)
.LBB0_1044:
	s_or_b64 exec, exec, s[6:7]
	s_waitcnt lgkmcnt(0)
	s_barrier
	s_branch .LBB0_1059

; __device__ __forceinline__ unsigned xb_ld(unsigned* p)              { return __hip_atomic_load(p, __ATOMIC_RELAXED, __HIP_MEMORY_SCOPE_AGENT); }
; __device__ __forceinline__ unsigned xb_add(unsigned* p, unsigned v) { return __hip_atomic_fetch_add(p, v, __ATOMIC_RELAXED, __HIP_MEMORY_SCOPE_AGENT); }
; #define XB_SPIN(cond, bar) do { unsigned _sp = 0; while (cond) { __builtin_amdgcn_s_sleep(1); \
;     if ((++_sp & 255u) == 0u) { if (xb_ld(&(bar)[XB_TMO])) break; if (_sp > XB_SPIN_CAP) { atomicAdd(&(bar)[XB_TMO], 1u); break; } } } } while (0)
; __device__ __forceinline__ void xcd_barrier(const XcdBarrier& b) {
;     ...
;             if (og + 1u == (tg + 1u) * nx) xb_add(&bar[XB_TOPGEN], 1u);
;             else XB_SPIN(xb_ld(&bar[XB_TOPGEN]) == tg, bar);
;             __builtin_amdgcn_fence(__ATOMIC_ACQUIRE, "agent");
;             xb_add(&bar[XB_XGEN(b.x)], 1u);
;             asm volatile("s_waitcnt vmcnt(0)" ::: "memory");
.LBB0_1216:
	s_or_b64 exec, exec, s[12:13]
	s_and_saveexec_b64 s[10:11], s[14:15]
	s_cbranch_execz .LBB0_1218
	global_atomic_add v[2:3], v252, off
.LBB0_1218:
	s_or_b64 exec, exec, s[10:11]
	s_waitcnt vmcnt(0)
	buffer_inv sc1
	s_waitcnt vmcnt(0)
.LBB0_1219:
	s_or_b64 exec, exec, s[6:7]
	s_waitcnt lgkmcnt(0)
	s_barrier
	s_branch .LBB0_1234

; __device__ __forceinline__ unsigned xb_ld(unsigned* p)              { return __hip_atomic_load(p, __ATOMIC_RELAXED, __HIP_MEMORY_SCOPE_AGENT); }
; __device__ __forceinline__ unsigned xb_add(unsigned* p, unsigned v) { return __hip_atomic_fetch_add(p, v, __ATOMIC_RELAXED, __HIP_MEMORY_SCOPE_AGENT); }
; #define XB_SPIN(cond, bar) do { unsigned _sp = 0; while (cond) { __builtin_amdgcn_s_sleep(1); \
;     if ((++_sp & 255u) == 0u) { if (xb_ld(&(bar)[XB_TMO])) break; if (_sp > XB_SPIN_CAP) { atomicAdd(&(bar)[XB_TMO], 1u); break; } } } } while (0)
; __device__ __forceinline__ void xcd_barrier(const XcdBarrier& b) {
;     ...
;         const unsigned old = xb_add(&bar[XB_XSUB(b.x)], 1u);
;         const unsigned gen = old / nloc;
;         if (old + 1u == (gen + 1u) * nloc) {
;             __builtin_amdgcn_fence(__ATOMIC_RELEASE, "agent");
;             asm volatile("s_waitcnt vmcnt(0)" ::: "memory");
;             const unsigned og = xb_add(&bar[XB_TOP], 1u);
;             const unsigned tg = og / nx;
;             if (og + 1u == (tg + 1u) * nx) xb_add(&bar[XB_TOPGEN], 1u);
;             else XB_SPIN(xb_ld(&bar[XB_TOPGEN]) == tg, bar);
;             __builtin_amdgcn_fence(__ATOMIC_ACQUIRE, "agent");
;             xb_add(&bar[XB_XGEN(b.x)], 1u);
;             asm volatile("s_waitcnt vmcnt(0)" ::: "memory");
;         } else {
;             XB_SPIN(xb_ld(&bar[XB_XGEN(b.x)]) == gen, bar);
.LBB0_1278:
	s_lshl_b32 s74, s90, 6
	s_lshl_b64 s[6:7], s[74:75], 2
	s_add_u32 s6, s88, s6
	s_addc_u32 s7, s89, s7
	v_mov_b32_e32 v1, 0x1000
	global_atomic_add v4, v1, v252, s[6:7] offset:1024 sc0
	v_cvt_f32_u32_e32 v1, v3
	v_sub_u32_e32 v5, 0, v3
	v_rcp_iflag_f32_e32 v1, v1
	s_nop 0
	v_mul_f32_e32 v1, 0x4f7ffffe, v1
	v_cvt_u32_f32_e32 v1, v1
	v_mul_lo_u32 v5, v5, v1
	v_mul_hi_u32 v5, v1, v5
	v_add_u32_e32 v1, v1, v5
	s_waitcnt vmcnt(0)
	v_mul_hi_u32 v1, v4, v1
	v_mul_lo_u32 v5, v1, v3
	v_sub_u32_e32 v5, v4, v5
	v_add_u32_e32 v6, 1, v1
	v_cmp_ge_u32_e32 vcc, v5, v3
	v_add_u32_e32 v4, 1, v4
	s_nop 0
	v_cndmask_b32_e32 v1, v1, v6, vcc
	v_sub_u32_e32 v6, v5, v3
	v_cndmask_b32_e32 v5, v5, v6, vcc
	v_add_u32_e32 v6, 1, v1
	v_cmp_ge_u32_e32 vcc, v5, v3
	s_nop 1
	v_cndmask_b32_e32 v1, v1, v6, vcc
	v_mul_lo_u32 v5, v3, v1
	v_add_u32_e32 v3, v5, v3
	v_cmp_ne_u32_e32 vcc, v4, v3
	s_and_saveexec_b64 s[8:9], vcc
	s_xor_b64 s[8:9], exec, s[8:9]
	s_cbranch_execz .LBB0_1291
	s_waitcnt lgkmcnt(0)
	s_add_u32 s12, s88, 0x3500
	s_addc_u32 s13, s89, 0
	global_load_dword v2, v0, s[12:13] sc1
	s_waitcnt vmcnt(0)
	v_cmp_eq_u32_e32 vcc, v2, v1
	s_and_saveexec_b64 s[10:11], vcc
	s_cbranch_execz .LBB0_1290
	s_mov_b32 s24, 1
	s_mov_b64 s[14:15], 0
	s_branch .LBB0_1282

; __device__ __forceinline__ unsigned xb_ld(unsigned* p)              { return __hip_atomic_load(p, __ATOMIC_RELAXED, __HIP_MEMORY_SCOPE_AGENT); }
; __device__ __forceinline__ unsigned xb_add(unsigned* p, unsigned v) { return __hip_atomic_fetch_add(p, v, __ATOMIC_RELAXED, __HIP_MEMORY_SCOPE_AGENT); }
; #define XB_SPIN(cond, bar) do { unsigned _sp = 0; while (cond) { __builtin_amdgcn_s_sleep(1); \
;     if ((++_sp & 255u) == 0u) { if (xb_ld(&(bar)[XB_TMO])) break; if (_sp > XB_SPIN_CAP) { atomicAdd(&(bar)[XB_TMO], 1u); break; } } } } while (0)
; __device__ __forceinline__ void xcd_barrier(const XcdBarrier& b) {
;     ...
;             if (og + 1u == (tg + 1u) * nx) xb_add(&bar[XB_TOPGEN], 1u);
;             else XB_SPIN(xb_ld(&bar[XB_TOPGEN]) == tg, bar);
;             __builtin_amdgcn_fence(__ATOMIC_ACQUIRE, "agent");
;             xb_add(&bar[XB_XGEN(b.x)], 1u);
;             asm volatile("s_waitcnt vmcnt(0)" ::: "memory");
.LBB0_1304:
	s_or_b64 exec, exec, s[10:11]
	s_and_saveexec_b64 s[8:9], s[12:13]
	s_cbranch_execz .LBB0_1306
	global_atomic_add v[2:3], v252, off
.LBB0_1306:
	s_or_b64 exec, exec, s[8:9]
	s_waitcnt vmcnt(0)
	buffer_inv sc1
	s_waitcnt vmcnt(0)
.LBB0_1307:
	s_or_b64 exec, exec, s[4:5]
	s_waitcnt lgkmcnt(0)
	s_barrier
	s_branch .LBB0_1322

; __device__ __forceinline__ unsigned xb_ld(unsigned* p)              { return __hip_atomic_load(p, __ATOMIC_RELAXED, __HIP_MEMORY_SCOPE_AGENT); }
; __device__ __forceinline__ unsigned xb_add(unsigned* p, unsigned v) { return __hip_atomic_fetch_add(p, v, __ATOMIC_RELAXED, __HIP_MEMORY_SCOPE_AGENT); }
; #define XB_SPIN(cond, bar) do { unsigned _sp = 0; while (cond) { __builtin_amdgcn_s_sleep(1); \
;     if ((++_sp & 255u) == 0u) { if (xb_ld(&(bar)[XB_TMO])) break; if (_sp > XB_SPIN_CAP) { atomicAdd(&(bar)[XB_TMO], 1u); break; } } } } while (0)
; __device__ __forceinline__ void xcd_barrier(const XcdBarrier& b) {
;     ...
;         const unsigned old = xb_add(&bar[XB_XSUB(b.x)], 1u);
;         const unsigned gen = old / nloc;
;         if (old + 1u == (gen + 1u) * nloc) {
;             __builtin_amdgcn_fence(__ATOMIC_RELEASE, "agent");
;             asm volatile("s_waitcnt vmcnt(0)" ::: "memory");
;             const unsigned og = xb_add(&bar[XB_TOP], 1u);
;             const unsigned tg = og / nx;
;             if (og + 1u == (tg + 1u) * nx) xb_add(&bar[XB_TOPGEN], 1u);
;             else XB_SPIN(xb_ld(&bar[XB_TOPGEN]) == tg, bar);
;             __builtin_amdgcn_fence(__ATOMIC_ACQUIRE, "agent");
;             xb_add(&bar[XB_XGEN(b.x)], 1u);
;             asm volatile("s_waitcnt vmcnt(0)" ::: "memory");
;         } else {
;             XB_SPIN(xb_ld(&bar[XB_XGEN(b.x)]) == gen, bar);
.LBB0_1402:
	s_lshl_b32 s74, s90, 6
	s_lshl_b64 s[6:7], s[74:75], 2
	s_add_u32 s6, s88, s6
	s_addc_u32 s7, s89, s7
	v_mov_b32_e32 v1, 0x1000
	global_atomic_add v4, v1, v252, s[6:7] offset:1024 sc0
	v_cvt_f32_u32_e32 v1, v3
	v_sub_u32_e32 v5, 0, v3
	v_rcp_iflag_f32_e32 v1, v1
	s_nop 0
	v_mul_f32_e32 v1, 0x4f7ffffe, v1
	v_cvt_u32_f32_e32 v1, v1
	v_mul_lo_u32 v5, v5, v1
	v_mul_hi_u32 v5, v1, v5
	v_add_u32_e32 v1, v1, v5
	s_waitcnt vmcnt(0)
	v_mul_hi_u32 v1, v4, v1
	v_mul_lo_u32 v5, v1, v3
	v_sub_u32_e32 v5, v4, v5
	v_add_u32_e32 v6, 1, v1
	v_cmp_ge_u32_e32 vcc, v5, v3
	v_add_u32_e32 v4, 1, v4
	s_nop 0
	v_cndmask_b32_e32 v1, v1, v6, vcc
	v_sub_u32_e32 v6, v5, v3
	v_cndmask_b32_e32 v5, v5, v6, vcc
	v_add_u32_e32 v6, 1, v1
	v_cmp_ge_u32_e32 vcc, v5, v3
	s_nop 1
	v_cndmask_b32_e32 v1, v1, v6, vcc
	v_mul_lo_u32 v5, v3, v1
	v_add_u32_e32 v3, v5, v3
	v_cmp_ne_u32_e32 vcc, v4, v3
	s_and_saveexec_b64 s[8:9], vcc
	s_xor_b64 s[8:9], exec, s[8:9]
	s_cbranch_execz .LBB0_1415
	s_waitcnt lgkmcnt(0)
	s_add_u32 s12, s88, 0x3500
	s_addc_u32 s13, s89, 0
	global_load_dword v2, v0, s[12:13] sc1
	s_waitcnt vmcnt(0)
	v_cmp_eq_u32_e32 vcc, v2, v1
	s_and_saveexec_b64 s[10:11], vcc
	s_cbranch_execz .LBB0_1414
	s_mov_b32 s2, 1
	s_mov_b64 s[14:15], 0
	s_branch .LBB0_1406

; __device__ __forceinline__ unsigned xb_ld(unsigned* p)              { return __hip_atomic_load(p, __ATOMIC_RELAXED, __HIP_MEMORY_SCOPE_AGENT); }
; __device__ __forceinline__ unsigned xb_add(unsigned* p, unsigned v) { return __hip_atomic_fetch_add(p, v, __ATOMIC_RELAXED, __HIP_MEMORY_SCOPE_AGENT); }
; #define XB_SPIN(cond, bar) do { unsigned _sp = 0; while (cond) { __builtin_amdgcn_s_sleep(1); \
;     if ((++_sp & 255u) == 0u) { if (xb_ld(&(bar)[XB_TMO])) break; if (_sp > XB_SPIN_CAP) { atomicAdd(&(bar)[XB_TMO], 1u); break; } } } } while (0)
; __device__ __forceinline__ void xcd_barrier(const XcdBarrier& b) {
;     ...
;             if (og + 1u == (tg + 1u) * nx) xb_add(&bar[XB_TOPGEN], 1u);
;             else XB_SPIN(xb_ld(&bar[XB_TOPGEN]) == tg, bar);
;             __builtin_amdgcn_fence(__ATOMIC_ACQUIRE, "agent");
;             xb_add(&bar[XB_XGEN(b.x)], 1u);
;             asm volatile("s_waitcnt vmcnt(0)" ::: "memory");
.LBB0_1428:
	s_or_b64 exec, exec, s[10:11]
	s_and_saveexec_b64 s[8:9], s[12:13]
	s_cbranch_execz .LBB0_1430
	global_atomic_add v[2:3], v252, off
.LBB0_1430:
	s_or_b64 exec, exec, s[8:9]
	s_waitcnt vmcnt(0)
	buffer_inv sc1
	s_waitcnt vmcnt(0)
.LBB0_1431:
	s_or_b64 exec, exec, s[4:5]
	s_waitcnt lgkmcnt(0)
	s_barrier
	s_branch .LBB0_1446

; __device__ __forceinline__ unsigned xb_ld(unsigned* p)              { return __hip_atomic_load(p, __ATOMIC_RELAXED, __HIP_MEMORY_SCOPE_AGENT); }
; __device__ __forceinline__ unsigned xb_add(unsigned* p, unsigned v) { return __hip_atomic_fetch_add(p, v, __ATOMIC_RELAXED, __HIP_MEMORY_SCOPE_AGENT); }
; #define XB_SPIN(cond, bar) do { unsigned _sp = 0; while (cond) { __builtin_amdgcn_s_sleep(1); \
;     if ((++_sp & 255u) == 0u) { if (xb_ld(&(bar)[XB_TMO])) break; if (_sp > XB_SPIN_CAP) { atomicAdd(&(bar)[XB_TMO], 1u); break; } } } } while (0)
; __device__ __forceinline__ void xcd_barrier(const XcdBarrier& b) {
;     ...
;         const unsigned old = xb_add(&bar[XB_XSUB(b.x)], 1u);
;         const unsigned gen = old / nloc;
;         if (old + 1u == (gen + 1u) * nloc) {
;             __builtin_amdgcn_fence(__ATOMIC_RELEASE, "agent");
;             asm volatile("s_waitcnt vmcnt(0)" ::: "memory");
;             const unsigned og = xb_add(&bar[XB_TOP], 1u);
;             const unsigned tg = og / nx;
;             if (og + 1u == (tg + 1u) * nx) xb_add(&bar[XB_TOPGEN], 1u);
;             else XB_SPIN(xb_ld(&bar[XB_TOPGEN]) == tg, bar);
;             __builtin_amdgcn_fence(__ATOMIC_ACQUIRE, "agent");
;             xb_add(&bar[XB_XGEN(b.x)], 1u);
;             asm volatile("s_waitcnt vmcnt(0)" ::: "memory");
;         } else {
;             XB_SPIN(xb_ld(&bar[XB_XGEN(b.x)]) == gen, bar);
.LBB0_1472:
	s_lshl_b32 s2, s68, 6
	s_mov_b32 s3, 0
	s_lshl_b64 s[2:3], s[2:3], 2
	s_add_u32 s2, s88, s2
	s_addc_u32 s3, s89, s3
	v_mov_b32_e32 v1, 0x1000
	v_mov_b32_e32 v3, 1
	global_atomic_add v3, v1, v3, s[2:3] offset:1024 sc0
	v_cvt_f32_u32_e32 v1, v2
	v_sub_u32_e32 v4, 0, v2
	v_rcp_iflag_f32_e32 v1, v1
	s_nop 0
	v_mul_f32_e32 v1, 0x4f7ffffe, v1
	v_cvt_u32_f32_e32 v1, v1
	v_mul_lo_u32 v4, v4, v1
	v_mul_hi_u32 v4, v1, v4
	v_add_u32_e32 v1, v1, v4
	s_waitcnt vmcnt(0)
	v_mul_hi_u32 v1, v3, v1
	v_mul_lo_u32 v4, v1, v2
	v_sub_u32_e32 v4, v3, v4
	v_add_u32_e32 v5, 1, v1
	v_cmp_ge_u32_e32 vcc, v4, v2
	v_add_u32_e32 v3, 1, v3
	s_nop 0
	v_cndmask_b32_e32 v1, v1, v5, vcc
	v_sub_u32_e32 v5, v4, v2
	v_cndmask_b32_e32 v4, v4, v5, vcc
	v_add_u32_e32 v5, 1, v1
	v_cmp_ge_u32_e32 vcc, v4, v2
	s_nop 1
	v_cndmask_b32_e32 v1, v1, v5, vcc
	v_mul_lo_u32 v4, v2, v1
	v_add_u32_e32 v2, v4, v2
	v_cmp_ne_u32_e32 vcc, v3, v2
	s_and_saveexec_b64 s[4:5], vcc
	s_xor_b64 s[6:7], exec, s[4:5]
	s_cbranch_execz .LBB0_1485
	s_waitcnt lgkmcnt(0)
	s_add_u32 s12, s88, 0x3500
	s_addc_u32 s13, s89, 0
	v_mov_b32_e32 v0, 0
	global_load_dword v0, v0, s[12:13] sc1
	s_waitcnt vmcnt(0)
	v_cmp_eq_u32_e32 vcc, v0, v1
	s_and_saveexec_b64 s[8:9], vcc
	s_cbranch_execz .LBB0_1484
	s_mov_b32 s4, 1
	s_mov_b64 s[14:15], 0
	v_mov_b32_e32 v0, 0
	s_branch .LBB0_1476

; __device__ __forceinline__ unsigned xb_ld(unsigned* p)              { return __hip_atomic_load(p, __ATOMIC_RELAXED, __HIP_MEMORY_SCOPE_AGENT); }
; __device__ __forceinline__ unsigned xb_add(unsigned* p, unsigned v) { return __hip_atomic_fetch_add(p, v, __ATOMIC_RELAXED, __HIP_MEMORY_SCOPE_AGENT); }
; #define XB_SPIN(cond, bar) do { unsigned _sp = 0; while (cond) { __builtin_amdgcn_s_sleep(1); \
;     if ((++_sp & 255u) == 0u) { if (xb_ld(&(bar)[XB_TMO])) break; if (_sp > XB_SPIN_CAP) { atomicAdd(&(bar)[XB_TMO], 1u); break; } } } } while (0)
; __device__ __forceinline__ void xcd_barrier(const XcdBarrier& b) {
;     ...
;             if (og + 1u == (tg + 1u) * nx) xb_add(&bar[XB_TOPGEN], 1u);
;             else XB_SPIN(xb_ld(&bar[XB_TOPGEN]) == tg, bar);
;             __builtin_amdgcn_fence(__ATOMIC_ACQUIRE, "agent");
;             xb_add(&bar[XB_XGEN(b.x)], 1u);
;             asm volatile("s_waitcnt vmcnt(0)" ::: "memory");
.LBB0_1500:
	s_or_b64 exec, exec, s[4:5]
	v_mov_b32_e32 v0, 0x2000
	v_mov_b32_e32 v1, 1
	s_waitcnt vmcnt(0)
	buffer_inv sc1
	s_waitcnt vmcnt(0)
